# dn
# speedup vs baseline: 1.0120x; 1.0049x over previous
; DEVI void ph_down(const Params& p, char* shm) {
;     ...
;     auto ep = [&](Acc256& acc) {
;       EPI_IDX;
; #pragma unroll
;       for (int ai = 0; ai < 2; ++ai)
; #pragma unroll
;         for (int m = 0; m < 4; ++m) {
;           int row = brow + ai * 128 + wr * 64 + m * 16 + fr;
;           int b = row >> 9, c = row & 511;
;           float gsc = selg[(b * 16 + e) * 512 + c] * (1.0f / W_DN_SCALE);
; #pragma unroll
;           for (int bj = 0; bj < 2; ++bj)
;             {
;               int col = bcol + bj * 128 + wc * 32 + (fq & 1) * 16 + (fq >> 1) * 8;
;               uint2 oa, ob;
;               oa.x = pack2(acc[ai][bj][m][0][0] * gsc, acc[ai][bj][m][0][1] * gsc);
;               oa.y = pack2(acc[ai][bj][m][0][2] * gsc, acc[ai][bj][m][0][3] * gsc);
;               ob.x = pack2(acc[ai][bj][m][1][0] * gsc, acc[ai][bj][m][1][1] * gsc);
;               ob.y = pack2(acc[ai][bj][m][1][2] * gsc, acc[ai][bj][m][1][3] * gsc);
;               *reinterpret_cast<uint4*>(Y + ((size_t)e * 4096 + row) * 1024 + col) = widen_pair(oa, ob);
;             }
;         }
;     };
.LBB0_1253:
	v_mov_b32_e32 v4, v214
	s_movk_i32 s17, 0xffc0
	v_and_b32_e32 v0, 15, v4
	v_ashrrev_i32_e32 v1, 2, v4
	v_and_or_b32 v0, v1, s17, v0
	v_add_u32_e32 v0, s35, v0
	v_lshrrev_b32_e32 v1, 1, v4
	v_lshrrev_b32_e32 v2, 5, v0
	v_and_b32_e32 v5, 0x60, v1
	v_lshrrev_b32_e32 v1, 2, v4
	v_and_b32_e32 v2, 0x7ffff0, v2
	v_and_b32_e32 v7, 8, v1
	v_and_b32_e32 v1, 0x1cf, v0
	v_add_u32_e32 v2, s16, v2
	v_lshl_or_b32 v2, v2, 9, v1
	v_ashrrev_i32_e32 v3, 31, v2
	v_lshl_add_u64 v[2:3], v[2:3], 2, s[80:81]
	v_mov_b32_e32 v252, v0
	v_lshrrev_b32_e32 v253, 5, v252
	v_and_b32_e32 v253, 0x7ffff0, v253
	v_and_b32_e32 v254, 0x1ff, v252
	v_add_u32_e32 v253, s16, v253
	v_lshl_or_b32 v254, v253, 9, v254
	v_ashrrev_i32_e32 v255, 31, v254
	v_lshl_add_u64 v[254:255], v[254:255], 2, s[80:81]
	global_load_dword v244, v[254:255], off
	v_add_u32_e32 v252, 0x10, v0
	v_lshrrev_b32_e32 v253, 5, v252
	v_and_b32_e32 v253, 0x7ffff0, v253
	v_and_b32_e32 v254, 0x1ff, v252
	v_add_u32_e32 v253, s16, v253
	v_lshl_or_b32 v254, v253, 9, v254
	v_ashrrev_i32_e32 v255, 31, v254
	v_lshl_add_u64 v[254:255], v[254:255], 2, s[80:81]
	global_load_dword v245, v[254:255], off
	v_add_u32_e32 v252, 0x20, v0
	v_lshrrev_b32_e32 v253, 5, v252
	v_and_b32_e32 v253, 0x7ffff0, v253
	v_and_b32_e32 v254, 0x1ff, v252
	v_add_u32_e32 v253, s16, v253
	v_lshl_or_b32 v254, v253, 9, v254
	v_ashrrev_i32_e32 v255, 31, v254
	v_lshl_add_u64 v[254:255], v[254:255], 2, s[80:81]
	global_load_dword v246, v[254:255], off
	v_add_u32_e32 v252, 0x30, v0
	v_lshrrev_b32_e32 v253, 5, v252
	v_and_b32_e32 v253, 0x7ffff0, v253
	v_and_b32_e32 v254, 0x1ff, v252
	v_add_u32_e32 v253, s16, v253
	v_lshl_or_b32 v254, v253, 9, v254
	v_ashrrev_i32_e32 v255, 31, v254
	v_lshl_add_u64 v[254:255], v[254:255], 2, s[80:81]
	global_load_dword v247, v[254:255], off
	v_add_u32_e32 v252, 0x80, v0
	v_lshrrev_b32_e32 v253, 5, v252
	v_and_b32_e32 v253, 0x7ffff0, v253
	v_and_b32_e32 v254, 0x1ff, v252
	v_add_u32_e32 v253, s16, v253
	v_lshl_or_b32 v254, v253, 9, v254
	v_ashrrev_i32_e32 v255, 31, v254
	v_lshl_add_u64 v[254:255], v[254:255], 2, s[80:81]
	global_load_dword v248, v[254:255], off
	v_add_u32_e32 v252, 0x90, v0
	v_lshrrev_b32_e32 v253, 5, v252
	v_and_b32_e32 v253, 0x7ffff0, v253
	v_and_b32_e32 v254, 0x1ff, v252
	v_add_u32_e32 v253, s16, v253
	v_lshl_or_b32 v254, v253, 9, v254
	v_ashrrev_i32_e32 v255, 31, v254
	v_lshl_add_u64 v[254:255], v[254:255], 2, s[80:81]
	global_load_dword v249, v[254:255], off
	v_add_u32_e32 v252, 0xa0, v0
	v_lshrrev_b32_e32 v253, 5, v252
	v_and_b32_e32 v253, 0x7ffff0, v253
	v_and_b32_e32 v254, 0x1ff, v252
	v_add_u32_e32 v253, s16, v253
	v_lshl_or_b32 v254, v253, 9, v254
	v_ashrrev_i32_e32 v255, 31, v254
	v_lshl_add_u64 v[254:255], v[254:255], 2, s[80:81]
	global_load_dword v250, v[254:255], off
	v_add_u32_e32 v252, 0xb0, v0
	v_lshrrev_b32_e32 v253, 5, v252
	v_and_b32_e32 v253, 0x7ffff0, v253
	v_and_b32_e32 v254, 0x1ff, v252
	v_add_u32_e32 v253, s16, v253
	v_lshl_or_b32 v254, v253, 9, v254
	v_ashrrev_i32_e32 v255, 31, v254
	v_lshl_add_u64 v[254:255], v[254:255], 2, s[80:81]
	global_load_dword v251, v[254:255], off
	s_waitcnt vmcnt(0)
	v_mov_b32_e32 v1, v244
	s_add_u32 s18, s86, s18
	s_addc_u32 s19, s87, s19
	s_add_i32 s26, s26, s27
	s_andn2_b64 vcc, exec, s[6:7]
	v_mul_f32_e32 v6, 0x3c800000, v1
	v_ashrrev_i32_e32 v1, 31, v0
	v_lshlrev_b64 v[8:9], 11, v[0:1]
	v_and_or_b32 v1, v4, 16, v5
	v_pk_mul_f32 v[2:3], v[188:189], v[6:7] op_sel_hi:[1,0]
	v_pk_mul_f32 v[4:5], v[190:191], v[6:7] op_sel_hi:[1,0]
	v_or3_b32 v1, v1, v7, s33
	v_cvt_pk_bf16_f32 v2, v2, v3
	v_cvt_pk_bf16_f32 v3, v4, v5
	v_pk_mul_f32 v[4:5], v[184:185], v[6:7] op_sel_hi:[1,0]
	v_pk_mul_f32 v[10:11], v[186:187], v[6:7] op_sel_hi:[1,0]
	v_cvt_pk_bf16_f32 v4, v4, v5
	v_cvt_pk_bf16_f32 v5, v10, v11
	v_lshl_add_u64 v[8:9], s[18:19], 0, v[8:9]
	v_lshlrev_b32_e32 v192, 1, v1
	v_permlane16_swap_b32_e32 v2, v4
	v_permlane16_swap_b32_e32 v3, v5
	v_lshl_add_u64 v[8:9], v[8:9], 0, v[192:193]
	global_store_dwordx4 v[8:9], v[2:5], off
	s_nop 1
	v_pk_mul_f32 v[2:3], v[180:181], v[6:7] op_sel_hi:[1,0]
	v_pk_mul_f32 v[4:5], v[182:183], v[6:7] op_sel_hi:[1,0]
	v_cvt_pk_bf16_f32 v2, v2, v3
	v_cvt_pk_bf16_f32 v3, v4, v5
	v_pk_mul_f32 v[4:5], v[176:177], v[6:7] op_sel_hi:[1,0]
	v_pk_mul_f32 v[6:7], v[178:179], v[6:7] op_sel_hi:[1,0]
	v_cvt_pk_bf16_f32 v4, v4, v5
	v_cvt_pk_bf16_f32 v5, v6, v7
	s_nop 0
	v_permlane16_swap_b32_e32 v2, v4
	v_permlane16_swap_b32_e32 v3, v5
	global_store_dwordx4 v[8:9], v[2:5], off offset:256
	s_nop 1
	v_add_u32_e32 v2, 16, v0
	v_lshrrev_b32_e32 v3, 5, v2
	v_and_b32_e32 v3, 0x7ffff0, v3
	v_and_b32_e32 v1, 0x1df, v2
	v_add_u32_e32 v3, s16, v3
	v_lshl_or_b32 v4, v3, 9, v1
	v_ashrrev_i32_e32 v5, 31, v4
	v_lshl_add_u64 v[4:5], v[4:5], 2, s[80:81]
	v_mov_b32_e32 v1, v245
	v_ashrrev_i32_e32 v3, 31, v2
	v_lshlrev_b64 v[8:9], 11, v[2:3]
	v_lshl_add_u64 v[8:9], s[18:19], 0, v[8:9]
	v_lshl_add_u64 v[8:9], v[8:9], 0, v[192:193]
	v_mul_f32_e32 v6, 0x3c800000, v1
	v_pk_mul_f32 v[2:3], v[172:173], v[6:7] op_sel_hi:[1,0]
	v_pk_mul_f32 v[4:5], v[174:175], v[6:7] op_sel_hi:[1,0]
	v_cvt_pk_bf16_f32 v2, v2, v3
	v_cvt_pk_bf16_f32 v3, v4, v5
	v_pk_mul_f32 v[4:5], v[168:169], v[6:7] op_sel_hi:[1,0]
	v_pk_mul_f32 v[10:11], v[170:171], v[6:7] op_sel_hi:[1,0]
	v_cvt_pk_bf16_f32 v4, v4, v5
	v_cvt_pk_bf16_f32 v5, v10, v11
	s_nop 0
	v_permlane16_swap_b32_e32 v2, v4
	v_permlane16_swap_b32_e32 v3, v5
	global_store_dwordx4 v[8:9], v[2:5], off
	s_nop 1
	v_pk_mul_f32 v[2:3], v[164:165], v[6:7] op_sel_hi:[1,0]
	v_pk_mul_f32 v[4:5], v[166:167], v[6:7] op_sel_hi:[1,0]
	v_cvt_pk_bf16_f32 v2, v2, v3
	v_cvt_pk_bf16_f32 v3, v4, v5
	v_pk_mul_f32 v[4:5], v[160:161], v[6:7] op_sel_hi:[1,0]
; DEVI void ph_down(const Params& p, char* shm) {
;     ...
;           int row = brow + ai * 128 + wr * 64 + m * 16 + fr;
;           int b = row >> 9, c = row & 511;
;           float gsc = selg[(b * 16 + e) * 512 + c] * (1.0f / W_DN_SCALE);
; #pragma unroll
;           for (int bj = 0; bj < 2; ++bj)
;             {
;               int col = bcol + bj * 128 + wc * 32 + (fq & 1) * 16 + (fq >> 1) * 8;
;               uint2 oa, ob;
;               oa.x = pack2(acc[ai][bj][m][0][0] * gsc, acc[ai][bj][m][0][1] * gsc);
;               oa.y = pack2(acc[ai][bj][m][0][2] * gsc, acc[ai][bj][m][0][3] * gsc);
;               ob.x = pack2(acc[ai][bj][m][1][0] * gsc, acc[ai][bj][m][1][1] * gsc);
;               ob.y = pack2(acc[ai][bj][m][1][2] * gsc, acc[ai][bj][m][1][3] * gsc);
;               *reinterpret_cast<uint4*>(Y + ((size_t)e * 4096 + row) * 1024 + col) = widen_pair(oa, ob);
;             }
	v_pk_mul_f32 v[6:7], v[162:163], v[6:7] op_sel_hi:[1,0]
	v_cvt_pk_bf16_f32 v4, v4, v5
	v_cvt_pk_bf16_f32 v5, v6, v7
	s_nop 0
	v_permlane16_swap_b32_e32 v2, v4
	v_permlane16_swap_b32_e32 v3, v5
	global_store_dwordx4 v[8:9], v[2:5], off offset:256
	s_nop 1
	v_add_u32_e32 v2, 32, v0
	v_lshrrev_b32_e32 v3, 5, v2
	v_and_b32_e32 v3, 0x7ffff0, v3
	v_and_b32_e32 v1, 0x1ef, v2
	v_add_u32_e32 v3, s16, v3
	v_lshl_or_b32 v4, v3, 9, v1
	v_ashrrev_i32_e32 v5, 31, v4
	v_lshl_add_u64 v[4:5], v[4:5], 2, s[80:81]
	v_mov_b32_e32 v1, v246
	v_ashrrev_i32_e32 v3, 31, v2
	v_lshlrev_b64 v[8:9], 11, v[2:3]
	v_lshl_add_u64 v[8:9], s[18:19], 0, v[8:9]
	v_lshl_add_u64 v[8:9], v[8:9], 0, v[192:193]
	v_mul_f32_e32 v6, 0x3c800000, v1
	v_pk_mul_f32 v[2:3], v[156:157], v[6:7] op_sel_hi:[1,0]
	v_pk_mul_f32 v[4:5], v[158:159], v[6:7] op_sel_hi:[1,0]
	v_cvt_pk_bf16_f32 v2, v2, v3
	v_cvt_pk_bf16_f32 v3, v4, v5
	v_pk_mul_f32 v[4:5], v[152:153], v[6:7] op_sel_hi:[1,0]
	v_pk_mul_f32 v[10:11], v[154:155], v[6:7] op_sel_hi:[1,0]
	v_cvt_pk_bf16_f32 v4, v4, v5
	v_cvt_pk_bf16_f32 v5, v10, v11
	s_nop 0
	v_permlane16_swap_b32_e32 v2, v4
	v_permlane16_swap_b32_e32 v3, v5
	global_store_dwordx4 v[8:9], v[2:5], off
	s_nop 1
	v_pk_mul_f32 v[2:3], v[148:149], v[6:7] op_sel_hi:[1,0]
	v_pk_mul_f32 v[4:5], v[150:151], v[6:7] op_sel_hi:[1,0]
	v_cvt_pk_bf16_f32 v2, v2, v3
	v_cvt_pk_bf16_f32 v3, v4, v5
	v_pk_mul_f32 v[4:5], v[144:145], v[6:7] op_sel_hi:[1,0]
	v_pk_mul_f32 v[6:7], v[146:147], v[6:7] op_sel_hi:[1,0]
	v_cvt_pk_bf16_f32 v4, v4, v5
	v_cvt_pk_bf16_f32 v5, v6, v7
	s_nop 0
	v_permlane16_swap_b32_e32 v2, v4
	v_permlane16_swap_b32_e32 v3, v5
	global_store_dwordx4 v[8:9], v[2:5], off offset:256
	s_nop 1
	v_add_u32_e32 v2, 48, v0
	v_lshrrev_b32_e32 v3, 5, v2
	v_and_b32_e32 v3, 0x7ffff0, v3
	v_and_b32_e32 v1, 0x1ff, v2
	v_add_u32_e32 v3, s16, v3
	v_lshl_or_b32 v4, v3, 9, v1
	v_ashrrev_i32_e32 v5, 31, v4
	v_lshl_add_u64 v[4:5], v[4:5], 2, s[80:81]
	v_mov_b32_e32 v1, v247
	v_ashrrev_i32_e32 v3, 31, v2
	v_lshlrev_b64 v[8:9], 11, v[2:3]
	v_lshl_add_u64 v[8:9], s[18:19], 0, v[8:9]
	v_lshl_add_u64 v[8:9], v[8:9], 0, v[192:193]
	v_mul_f32_e32 v6, 0x3c800000, v1
	v_pk_mul_f32 v[2:3], v[140:141], v[6:7] op_sel_hi:[1,0]
	v_pk_mul_f32 v[4:5], v[142:143], v[6:7] op_sel_hi:[1,0]
	v_cvt_pk_bf16_f32 v2, v2, v3
	v_cvt_pk_bf16_f32 v3, v4, v5
	v_pk_mul_f32 v[4:5], v[136:137], v[6:7] op_sel_hi:[1,0]
	v_pk_mul_f32 v[10:11], v[138:139], v[6:7] op_sel_hi:[1,0]
	v_cvt_pk_bf16_f32 v4, v4, v5
	v_cvt_pk_bf16_f32 v5, v10, v11
	s_nop 0
	v_permlane16_swap_b32_e32 v2, v4
	v_permlane16_swap_b32_e32 v3, v5
	global_store_dwordx4 v[8:9], v[2:5], off
	s_nop 1
	v_pk_mul_f32 v[2:3], v[132:133], v[6:7] op_sel_hi:[1,0]
	v_pk_mul_f32 v[4:5], v[134:135], v[6:7] op_sel_hi:[1,0]
	v_cvt_pk_bf16_f32 v2, v2, v3
	v_cvt_pk_bf16_f32 v3, v4, v5
	v_pk_mul_f32 v[4:5], v[128:129], v[6:7] op_sel_hi:[1,0]
	v_pk_mul_f32 v[6:7], v[130:131], v[6:7] op_sel_hi:[1,0]
	v_cvt_pk_bf16_f32 v4, v4, v5
	v_cvt_pk_bf16_f32 v5, v6, v7
	s_nop 0
	v_permlane16_swap_b32_e32 v2, v4
	v_permlane16_swap_b32_e32 v3, v5
	global_store_dwordx4 v[8:9], v[2:5], off offset:256
	s_nop 1
	v_add_u32_e32 v2, 0x80, v0
	v_lshrrev_b32_e32 v3, 5, v2
	v_and_b32_e32 v3, 0x7ffff0, v3
	v_and_b32_e32 v1, 0x1cf, v2
	v_add_u32_e32 v3, s16, v3
	v_lshl_or_b32 v4, v3, 9, v1
	v_ashrrev_i32_e32 v5, 31, v4
	v_lshl_add_u64 v[4:5], v[4:5], 2, s[80:81]
	v_mov_b32_e32 v1, v248
	v_ashrrev_i32_e32 v3, 31, v2
	v_lshlrev_b64 v[8:9], 11, v[2:3]
	v_lshl_add_u64 v[8:9], s[18:19], 0, v[8:9]
	v_lshl_add_u64 v[8:9], v[8:9], 0, v[192:193]
	v_mul_f32_e32 v6, 0x3c800000, v1
	v_pk_mul_f32 v[2:3], v[124:125], v[6:7] op_sel_hi:[1,0]
	v_pk_mul_f32 v[4:5], v[126:127], v[6:7] op_sel_hi:[1,0]
	v_cvt_pk_bf16_f32 v2, v2, v3
	v_cvt_pk_bf16_f32 v3, v4, v5
	v_pk_mul_f32 v[4:5], v[120:121], v[6:7] op_sel_hi:[1,0]
	v_pk_mul_f32 v[10:11], v[122:123], v[6:7] op_sel_hi:[1,0]
	v_cvt_pk_bf16_f32 v4, v4, v5
	v_cvt_pk_bf16_f32 v5, v10, v11
	s_nop 0
	v_permlane16_swap_b32_e32 v2, v4
	v_permlane16_swap_b32_e32 v3, v5
	global_store_dwordx4 v[8:9], v[2:5], off
	s_nop 1
	v_pk_mul_f32 v[2:3], v[116:117], v[6:7] op_sel_hi:[1,0]
	v_pk_mul_f32 v[4:5], v[118:119], v[6:7] op_sel_hi:[1,0]
	v_cvt_pk_bf16_f32 v2, v2, v3
	v_cvt_pk_bf16_f32 v3, v4, v5
	v_pk_mul_f32 v[4:5], v[112:113], v[6:7] op_sel_hi:[1,0]
	v_pk_mul_f32 v[6:7], v[114:115], v[6:7] op_sel_hi:[1,0]
	v_cvt_pk_bf16_f32 v4, v4, v5
	v_cvt_pk_bf16_f32 v5, v6, v7
	s_nop 0
; DEVI void ph_down(const Params& p, char* shm) {
;     ...
;         for (int m = 0; m < 4; ++m) {
;           int row = brow + ai * 128 + wr * 64 + m * 16 + fr;
;           int b = row >> 9, c = row & 511;
;           float gsc = selg[(b * 16 + e) * 512 + c] * (1.0f / W_DN_SCALE);
; #pragma unroll
;           for (int bj = 0; bj < 2; ++bj)
;             {
;               int col = bcol + bj * 128 + wc * 32 + (fq & 1) * 16 + (fq >> 1) * 8;
;               uint2 oa, ob;
;               oa.x = pack2(acc[ai][bj][m][0][0] * gsc, acc[ai][bj][m][0][1] * gsc);
;               oa.y = pack2(acc[ai][bj][m][0][2] * gsc, acc[ai][bj][m][0][3] * gsc);
;               ob.x = pack2(acc[ai][bj][m][1][0] * gsc, acc[ai][bj][m][1][1] * gsc);
;               ob.y = pack2(acc[ai][bj][m][1][2] * gsc, acc[ai][bj][m][1][3] * gsc);
;               *reinterpret_cast<uint4*>(Y + ((size_t)e * 4096 + row) * 1024 + col) = widen_pair(oa, ob);
;             }
	v_permlane16_swap_b32_e32 v2, v4
	v_permlane16_swap_b32_e32 v3, v5
	global_store_dwordx4 v[8:9], v[2:5], off offset:256
	s_nop 1
	v_add_u32_e32 v2, 0x90, v0
	v_lshrrev_b32_e32 v3, 5, v2
	v_and_b32_e32 v3, 0x7ffff0, v3
	v_and_b32_e32 v1, 0x1df, v2
	v_add_u32_e32 v3, s16, v3
	v_lshl_or_b32 v4, v3, 9, v1
	v_ashrrev_i32_e32 v5, 31, v4
	v_lshl_add_u64 v[4:5], v[4:5], 2, s[80:81]
	v_mov_b32_e32 v1, v249
	v_ashrrev_i32_e32 v3, 31, v2
	v_lshlrev_b64 v[8:9], 11, v[2:3]
	v_lshl_add_u64 v[8:9], s[18:19], 0, v[8:9]
	v_lshl_add_u64 v[8:9], v[8:9], 0, v[192:193]
	v_mul_f32_e32 v6, 0x3c800000, v1
	v_pk_mul_f32 v[2:3], v[108:109], v[6:7] op_sel_hi:[1,0]
	v_pk_mul_f32 v[4:5], v[110:111], v[6:7] op_sel_hi:[1,0]
	v_cvt_pk_bf16_f32 v2, v2, v3
	v_cvt_pk_bf16_f32 v3, v4, v5
	v_pk_mul_f32 v[4:5], v[104:105], v[6:7] op_sel_hi:[1,0]
	v_pk_mul_f32 v[10:11], v[106:107], v[6:7] op_sel_hi:[1,0]
	v_cvt_pk_bf16_f32 v4, v4, v5
	v_cvt_pk_bf16_f32 v5, v10, v11
	s_nop 0
	v_permlane16_swap_b32_e32 v2, v4
	v_permlane16_swap_b32_e32 v3, v5
	global_store_dwordx4 v[8:9], v[2:5], off
	s_nop 1
	v_pk_mul_f32 v[2:3], v[100:101], v[6:7] op_sel_hi:[1,0]
	v_pk_mul_f32 v[4:5], v[102:103], v[6:7] op_sel_hi:[1,0]
	v_cvt_pk_bf16_f32 v2, v2, v3
	v_cvt_pk_bf16_f32 v3, v4, v5
	v_pk_mul_f32 v[4:5], v[96:97], v[6:7] op_sel_hi:[1,0]
	v_pk_mul_f32 v[6:7], v[98:99], v[6:7] op_sel_hi:[1,0]
	v_cvt_pk_bf16_f32 v4, v4, v5
	v_cvt_pk_bf16_f32 v5, v6, v7
	s_nop 0
	v_permlane16_swap_b32_e32 v2, v4
	v_permlane16_swap_b32_e32 v3, v5
	global_store_dwordx4 v[8:9], v[2:5], off offset:256
	s_nop 1
	v_add_u32_e32 v2, 0xa0, v0
	v_lshrrev_b32_e32 v3, 5, v2
	v_and_b32_e32 v3, 0x7ffff0, v3
	v_and_b32_e32 v1, 0x1ef, v2
	v_add_u32_e32 v3, s16, v3
	v_lshl_or_b32 v4, v3, 9, v1
	v_ashrrev_i32_e32 v5, 31, v4
	v_lshl_add_u64 v[4:5], v[4:5], 2, s[80:81]
	v_mov_b32_e32 v1, v250
	v_ashrrev_i32_e32 v3, 31, v2
	v_lshlrev_b64 v[8:9], 11, v[2:3]
	v_lshl_add_u64 v[8:9], s[18:19], 0, v[8:9]
	v_lshl_add_u64 v[8:9], v[8:9], 0, v[192:193]
	v_add_u32_e32 v0, 0xb0, v0
	v_mul_f32_e32 v6, 0x3c800000, v1
	v_pk_mul_f32 v[2:3], v[92:93], v[6:7] op_sel_hi:[1,0]
	v_pk_mul_f32 v[4:5], v[94:95], v[6:7] op_sel_hi:[1,0]
	v_cvt_pk_bf16_f32 v2, v2, v3
	v_cvt_pk_bf16_f32 v3, v4, v5
	v_pk_mul_f32 v[4:5], v[88:89], v[6:7] op_sel_hi:[1,0]
	v_pk_mul_f32 v[10:11], v[90:91], v[6:7] op_sel_hi:[1,0]
	v_cvt_pk_bf16_f32 v4, v4, v5
	v_cvt_pk_bf16_f32 v5, v10, v11
	s_nop 0
	v_permlane16_swap_b32_e32 v2, v4
	v_permlane16_swap_b32_e32 v3, v5
	global_store_dwordx4 v[8:9], v[2:5], off
	v_and_b32_e32 v1, 0x1ff, v0
	s_nop 0
	v_pk_mul_f32 v[2:3], v[84:85], v[6:7] op_sel_hi:[1,0]
	v_pk_mul_f32 v[4:5], v[86:87], v[6:7] op_sel_hi:[1,0]
	v_cvt_pk_bf16_f32 v2, v2, v3
	v_cvt_pk_bf16_f32 v3, v4, v5
	v_pk_mul_f32 v[4:5], v[80:81], v[6:7] op_sel_hi:[1,0]
	v_pk_mul_f32 v[6:7], v[82:83], v[6:7] op_sel_hi:[1,0]
	v_cvt_pk_bf16_f32 v4, v4, v5
	v_cvt_pk_bf16_f32 v5, v6, v7
	s_nop 0
	v_permlane16_swap_b32_e32 v2, v4
	v_permlane16_swap_b32_e32 v3, v5
	global_store_dwordx4 v[8:9], v[2:5], off offset:256
	s_nop 1
	v_lshrrev_b32_e32 v2, 5, v0
	v_and_b32_e32 v2, 0x7ffff0, v2
	v_add_u32_e32 v2, s16, v2
	v_lshl_or_b32 v2, v2, 9, v1
	v_ashrrev_i32_e32 v3, 31, v2
	v_lshl_add_u64 v[2:3], v[2:3], 2, s[80:81]
	v_mov_b32_e32 v1, v251
	s_mov_b64 s[16:17], 0
	v_mul_f32_e32 v4, 0x3c800000, v1
	v_ashrrev_i32_e32 v1, 31, v0
	v_lshlrev_b64 v[6:7], 11, v[0:1]
	v_pk_mul_f32 v[0:1], v[76:77], v[4:5] op_sel_hi:[1,0]
	v_pk_mul_f32 v[2:3], v[78:79], v[4:5] op_sel_hi:[1,0]
	v_cvt_pk_bf16_f32 v0, v0, v1
	v_cvt_pk_bf16_f32 v1, v2, v3
	v_pk_mul_f32 v[2:3], v[72:73], v[4:5] op_sel_hi:[1,0]
	v_pk_mul_f32 v[8:9], v[74:75], v[4:5] op_sel_hi:[1,0]
	v_cvt_pk_bf16_f32 v2, v2, v3
	v_cvt_pk_bf16_f32 v3, v8, v9
	v_lshl_add_u64 v[6:7], s[18:19], 0, v[6:7]
	v_permlane16_swap_b32_e32 v0, v2
	v_permlane16_swap_b32_e32 v1, v3
	v_lshl_add_u64 v[6:7], v[6:7], 0, v[192:193]
	global_store_dwordx4 v[6:7], v[0:3], off
	s_nop 1
	v_pk_mul_f32 v[0:1], v[68:69], v[4:5] op_sel_hi:[1,0]
	v_pk_mul_f32 v[2:3], v[70:71], v[4:5] op_sel_hi:[1,0]
	v_cvt_pk_bf16_f32 v0, v0, v1
	v_cvt_pk_bf16_f32 v1, v2, v3
	v_pk_mul_f32 v[2:3], v[64:65], v[4:5] op_sel_hi:[1,0]
	v_pk_mul_f32 v[4:5], v[66:67], v[4:5] op_sel_hi:[1,0]
	v_cvt_pk_bf16_f32 v2, v2, v3
	v_cvt_pk_bf16_f32 v3, v4, v5
	s_nop 0
	v_permlane16_swap_b32_e32 v0, v2
	v_permlane16_swap_b32_e32 v1, v3
	global_store_dwordx4 v[6:7], v[0:3], off offset:256
	s_cbranch_vccz .LBB0_1286

; DEVI void ph_down(const Params& p, char* shm) {
;     ...
;     auto ep = [&](Acc256& acc) {
;       EPI_IDX;
; #pragma unroll
;       for (int ai = 0; ai < 2; ++ai)
; #pragma unroll
;         for (int m = 0; m < 4; ++m) {
;           int row = brow + ai * 128 + wr * 64 + m * 16 + fr;
;           int b = row >> 9, c = row & 511;
;           float gsc = selg[(b * 16 + e) * 512 + c] * (1.0f / W_DN_SCALE);
; #pragma unroll
;           for (int bj = 0; bj < 2; ++bj)
;             {
;               int col = bcol + bj * 128 + wc * 32 + (fq & 1) * 16 + (fq >> 1) * 8;
;               uint2 oa, ob;
;               oa.x = pack2(acc[ai][bj][m][0][0] * gsc, acc[ai][bj][m][0][1] * gsc);
;               oa.y = pack2(acc[ai][bj][m][0][2] * gsc, acc[ai][bj][m][0][3] * gsc);
;               ob.x = pack2(acc[ai][bj][m][1][0] * gsc, acc[ai][bj][m][1][1] * gsc);
;               ob.y = pack2(acc[ai][bj][m][1][2] * gsc, acc[ai][bj][m][1][3] * gsc);
;               *reinterpret_cast<uint4*>(Y + ((size_t)e * 4096 + row) * 1024 + col) = widen_pair(oa, ob);
;             }
.LBB0_2089:
	v_mov_b32_e32 v1, v214
	s_add_u32 s56, s86, s56
	v_and_b32_e32 v0, 15, v1
	v_ashrrev_i32_e32 v2, 2, v1
	v_and_or_b32 v0, v2, s74, v0
	v_add_u32_e32 v0, s77, v0
	v_lshrrev_b32_e32 v3, 5, v0
	v_and_b32_e32 v3, 0x7ffff0, v3
	v_and_b32_e32 v2, 0x1cf, v0
	v_add_u32_e32 v3, s54, v3
	v_lshl_or_b32 v2, v3, 9, v2
	v_ashrrev_i32_e32 v3, 31, v2
	v_lshl_add_u64 v[2:3], v[2:3], 2, s[80:81]
	v_mov_b32_e32 v252, v0
	v_lshrrev_b32_e32 v253, 5, v252
	v_and_b32_e32 v253, 0x7ffff0, v253
	v_and_b32_e32 v254, 0x1ff, v252
	v_add_u32_e32 v253, s54, v253
	v_lshl_or_b32 v254, v253, 9, v254
	v_ashrrev_i32_e32 v255, 31, v254
	v_lshl_add_u64 v[254:255], v[254:255], 2, s[80:81]
	global_load_dword v244, v[254:255], off
	v_add_u32_e32 v252, 0x10, v0
	v_lshrrev_b32_e32 v253, 5, v252
	v_and_b32_e32 v253, 0x7ffff0, v253
	v_and_b32_e32 v254, 0x1ff, v252
	v_add_u32_e32 v253, s54, v253
	v_lshl_or_b32 v254, v253, 9, v254
	v_ashrrev_i32_e32 v255, 31, v254
	v_lshl_add_u64 v[254:255], v[254:255], 2, s[80:81]
	global_load_dword v245, v[254:255], off
	v_add_u32_e32 v252, 0x20, v0
	v_lshrrev_b32_e32 v253, 5, v252
	v_and_b32_e32 v253, 0x7ffff0, v253
	v_and_b32_e32 v254, 0x1ff, v252
	v_add_u32_e32 v253, s54, v253
	v_lshl_or_b32 v254, v253, 9, v254
	v_ashrrev_i32_e32 v255, 31, v254
	v_lshl_add_u64 v[254:255], v[254:255], 2, s[80:81]
	global_load_dword v246, v[254:255], off
	v_add_u32_e32 v252, 0x30, v0
	v_lshrrev_b32_e32 v253, 5, v252
	v_and_b32_e32 v253, 0x7ffff0, v253
	v_and_b32_e32 v254, 0x1ff, v252
	v_add_u32_e32 v253, s54, v253
	v_lshl_or_b32 v254, v253, 9, v254
	v_ashrrev_i32_e32 v255, 31, v254
	v_lshl_add_u64 v[254:255], v[254:255], 2, s[80:81]
	global_load_dword v247, v[254:255], off
	v_add_u32_e32 v252, 0x80, v0
	v_lshrrev_b32_e32 v253, 5, v252
	v_and_b32_e32 v253, 0x7ffff0, v253
	v_and_b32_e32 v254, 0x1ff, v252
	v_add_u32_e32 v253, s54, v253
	v_lshl_or_b32 v254, v253, 9, v254
	v_ashrrev_i32_e32 v255, 31, v254
	v_lshl_add_u64 v[254:255], v[254:255], 2, s[80:81]
	global_load_dword v248, v[254:255], off
	v_add_u32_e32 v252, 0x90, v0
	v_lshrrev_b32_e32 v253, 5, v252
	v_and_b32_e32 v253, 0x7ffff0, v253
	v_and_b32_e32 v254, 0x1ff, v252
	v_add_u32_e32 v253, s54, v253
	v_lshl_or_b32 v254, v253, 9, v254
	v_ashrrev_i32_e32 v255, 31, v254
	v_lshl_add_u64 v[254:255], v[254:255], 2, s[80:81]
	global_load_dword v249, v[254:255], off
	v_add_u32_e32 v252, 0xa0, v0
	v_lshrrev_b32_e32 v253, 5, v252
	v_and_b32_e32 v253, 0x7ffff0, v253
	v_and_b32_e32 v254, 0x1ff, v252
	v_add_u32_e32 v253, s54, v253
	v_lshl_or_b32 v254, v253, 9, v254
	v_ashrrev_i32_e32 v255, 31, v254
	v_lshl_add_u64 v[254:255], v[254:255], 2, s[80:81]
	global_load_dword v250, v[254:255], off
	v_add_u32_e32 v252, 0xb0, v0
	v_lshrrev_b32_e32 v253, 5, v252
	v_and_b32_e32 v253, 0x7ffff0, v253
	v_and_b32_e32 v254, 0x1ff, v252
	v_add_u32_e32 v253, s54, v253
	v_lshl_or_b32 v254, v253, 9, v254
	v_ashrrev_i32_e32 v255, 31, v254
	v_lshl_add_u64 v[254:255], v[254:255], 2, s[80:81]
	global_load_dword v251, v[254:255], off
	s_waitcnt vmcnt(0)
	v_mov_b32_e32 v4, v244
	v_lshrrev_b32_e32 v2, 1, v1
	v_lshrrev_b32_e32 v3, 2, v1
	v_and_b32_e32 v2, 0x60, v2
	v_and_b32_e32 v3, 8, v3
	v_and_or_b32 v2, v1, 16, v2
	v_ashrrev_i32_e32 v1, 31, v0
	v_or3_b32 v5, v2, v3, s76
	v_add_u32_e32 v10, 16, v0
	s_addc_u32 s57, s87, s57
	v_lshlrev_b64 v[2:3], 11, v[0:1]
	v_lshlrev_b32_e32 v192, 1, v5
	v_lshrrev_b32_e32 v5, 5, v10
	v_lshl_add_u64 v[2:3], s[56:57], 0, v[2:3]
	v_and_b32_e32 v5, 0x7ffff0, v5
	v_and_b32_e32 v1, 0x1df, v10
	v_lshl_add_u64 v[12:13], v[2:3], 0, v[192:193]
	v_add_u32_e32 v2, s54, v5
	v_lshl_or_b32 v2, v2, 9, v1
	v_ashrrev_i32_e32 v3, 31, v2
	v_lshl_add_u64 v[14:15], v[2:3], 2, s[80:81]
	v_ashrrev_i32_e32 v11, 31, v10
	s_add_i32 s33, s33, s66
	s_andn2_b64 vcc, exec, s[4:5]
	s_mov_b64 s[4:5], 0
	v_mul_f32_e32 v2, 0x3c800000, v4
	v_pk_mul_f32 v[4:5], v[188:189], v[2:3] op_sel_hi:[1,0]
	v_pk_mul_f32 v[6:7], v[190:191], v[2:3] op_sel_hi:[1,0]
	v_pk_mul_f32 v[8:9], v[184:185], v[2:3] op_sel_hi:[1,0]
	v_pk_mul_f32 v[16:17], v[186:187], v[2:3] op_sel_hi:[1,0]
	v_pk_mul_f32 v[18:19], v[180:181], v[2:3] op_sel_hi:[1,0]
	v_pk_mul_f32 v[20:21], v[182:183], v[2:3] op_sel_hi:[1,0]
	v_pk_mul_f32 v[22:23], v[176:177], v[2:3] op_sel_hi:[1,0]
	v_pk_mul_f32 v[24:25], v[178:179], v[2:3] op_sel_hi:[1,0]
	v_cvt_pk_bf16_f32 v2, v4, v5
	v_cvt_pk_bf16_f32 v3, v6, v7
	v_cvt_pk_bf16_f32 v4, v8, v9
	v_cvt_pk_bf16_f32 v5, v16, v17
	v_cvt_pk_bf16_f32 v6, v18, v19
	v_cvt_pk_bf16_f32 v7, v20, v21
	v_cvt_pk_bf16_f32 v8, v22, v23
	v_cvt_pk_bf16_f32 v9, v24, v25
	v_permlane16_swap_b32_e32 v2, v4
	v_permlane16_swap_b32_e32 v3, v5
	v_permlane16_swap_b32_e32 v6, v8
	v_permlane16_swap_b32_e32 v7, v9
	global_store_dwordx4 v[12:13], v[2:5], off
	global_store_dwordx4 v[12:13], v[6:9], off offset:256
	v_mov_b32_e32 v1, v245
	v_add_u32_e32 v12, 32, v0
	v_lshrrev_b32_e32 v5, 5, v12
	v_lshlrev_b64 v[2:3], 11, v[10:11]
	v_and_b32_e32 v5, 0x7ffff0, v5
	v_and_b32_e32 v4, 0x1ef, v12
	v_lshl_add_u64 v[2:3], s[56:57], 0, v[2:3]
	v_add_u32_e32 v5, s54, v5
	v_lshl_add_u64 v[10:11], v[2:3], 0, v[192:193]
	v_lshl_or_b32 v2, v5, 9, v4
	v_ashrrev_i32_e32 v3, 31, v2
	v_lshl_add_u64 v[14:15], v[2:3], 2, s[80:81]
	v_ashrrev_i32_e32 v13, 31, v12
	v_mul_f32_e32 v2, 0x3c800000, v1
	v_pk_mul_f32 v[4:5], v[172:173], v[2:3] op_sel_hi:[1,0]
	v_pk_mul_f32 v[6:7], v[174:175], v[2:3] op_sel_hi:[1,0]
	v_pk_mul_f32 v[8:9], v[168:169], v[2:3] op_sel_hi:[1,0]
	v_pk_mul_f32 v[16:17], v[170:171], v[2:3] op_sel_hi:[1,0]
	v_pk_mul_f32 v[18:19], v[164:165], v[2:3] op_sel_hi:[1,0]
	v_pk_mul_f32 v[20:21], v[166:167], v[2:3] op_sel_hi:[1,0]
	v_pk_mul_f32 v[22:23], v[160:161], v[2:3] op_sel_hi:[1,0]
; DEVI void ph_down(const Params& p, char* shm) {
;     ...
;         for (int m = 0; m < 4; ++m) {
;           int row = brow + ai * 128 + wr * 64 + m * 16 + fr;
;           int b = row >> 9, c = row & 511;
;           float gsc = selg[(b * 16 + e) * 512 + c] * (1.0f / W_DN_SCALE);
; #pragma unroll
;           for (int bj = 0; bj < 2; ++bj)
;             {
;               int col = bcol + bj * 128 + wc * 32 + (fq & 1) * 16 + (fq >> 1) * 8;
;               uint2 oa, ob;
;               oa.x = pack2(acc[ai][bj][m][0][0] * gsc, acc[ai][bj][m][0][1] * gsc);
;               oa.y = pack2(acc[ai][bj][m][0][2] * gsc, acc[ai][bj][m][0][3] * gsc);
;               ob.x = pack2(acc[ai][bj][m][1][0] * gsc, acc[ai][bj][m][1][1] * gsc);
;               ob.y = pack2(acc[ai][bj][m][1][2] * gsc, acc[ai][bj][m][1][3] * gsc);
;               *reinterpret_cast<uint4*>(Y + ((size_t)e * 4096 + row) * 1024 + col) = widen_pair(oa, ob);
;             }
	v_pk_mul_f32 v[24:25], v[162:163], v[2:3] op_sel_hi:[1,0]
	v_cvt_pk_bf16_f32 v2, v4, v5
	v_cvt_pk_bf16_f32 v3, v6, v7
	v_cvt_pk_bf16_f32 v4, v8, v9
	v_cvt_pk_bf16_f32 v5, v16, v17
	v_cvt_pk_bf16_f32 v6, v18, v19
	v_cvt_pk_bf16_f32 v7, v20, v21
	v_cvt_pk_bf16_f32 v8, v22, v23
	v_cvt_pk_bf16_f32 v9, v24, v25
	v_permlane16_swap_b32_e32 v2, v4
	v_permlane16_swap_b32_e32 v3, v5
	v_permlane16_swap_b32_e32 v6, v8
	v_permlane16_swap_b32_e32 v7, v9
	global_store_dwordx4 v[10:11], v[2:5], off
	global_store_dwordx4 v[10:11], v[6:9], off offset:256
	v_mov_b32_e32 v1, v246
	v_add_u32_e32 v10, 48, v0
	v_lshrrev_b32_e32 v5, 5, v10
	v_lshlrev_b64 v[2:3], 11, v[12:13]
	v_and_b32_e32 v5, 0x7ffff0, v5
	v_and_b32_e32 v4, 0x1ff, v10
	v_lshl_add_u64 v[2:3], s[56:57], 0, v[2:3]
	v_add_u32_e32 v5, s54, v5
	v_lshl_add_u64 v[12:13], v[2:3], 0, v[192:193]
	v_lshl_or_b32 v2, v5, 9, v4
	v_ashrrev_i32_e32 v3, 31, v2
	v_lshl_add_u64 v[14:15], v[2:3], 2, s[80:81]
	v_ashrrev_i32_e32 v11, 31, v10
	v_mul_f32_e32 v2, 0x3c800000, v1
	v_pk_mul_f32 v[4:5], v[156:157], v[2:3] op_sel_hi:[1,0]
	v_pk_mul_f32 v[6:7], v[158:159], v[2:3] op_sel_hi:[1,0]
	v_pk_mul_f32 v[8:9], v[152:153], v[2:3] op_sel_hi:[1,0]
	v_pk_mul_f32 v[16:17], v[154:155], v[2:3] op_sel_hi:[1,0]
	v_pk_mul_f32 v[18:19], v[148:149], v[2:3] op_sel_hi:[1,0]
	v_pk_mul_f32 v[20:21], v[150:151], v[2:3] op_sel_hi:[1,0]
	v_pk_mul_f32 v[22:23], v[144:145], v[2:3] op_sel_hi:[1,0]
	v_pk_mul_f32 v[24:25], v[146:147], v[2:3] op_sel_hi:[1,0]
	v_cvt_pk_bf16_f32 v2, v4, v5
	v_cvt_pk_bf16_f32 v3, v6, v7
	v_cvt_pk_bf16_f32 v4, v8, v9
	v_cvt_pk_bf16_f32 v5, v16, v17
	v_cvt_pk_bf16_f32 v6, v18, v19
	v_cvt_pk_bf16_f32 v7, v20, v21
	v_cvt_pk_bf16_f32 v8, v22, v23
	v_cvt_pk_bf16_f32 v9, v24, v25
	v_permlane16_swap_b32_e32 v2, v4
	v_permlane16_swap_b32_e32 v3, v5
	v_permlane16_swap_b32_e32 v6, v8
	v_permlane16_swap_b32_e32 v7, v9
	global_store_dwordx4 v[12:13], v[2:5], off
	global_store_dwordx4 v[12:13], v[6:9], off offset:256
	v_mov_b32_e32 v1, v247
	v_add_u32_e32 v12, 0x80, v0
	v_lshrrev_b32_e32 v5, 5, v12
	v_lshlrev_b64 v[2:3], 11, v[10:11]
	v_and_b32_e32 v5, 0x7ffff0, v5
	v_and_b32_e32 v4, 0x1cf, v12
	v_lshl_add_u64 v[2:3], s[56:57], 0, v[2:3]
	v_add_u32_e32 v5, s54, v5
	v_lshl_add_u64 v[10:11], v[2:3], 0, v[192:193]
	v_lshl_or_b32 v2, v5, 9, v4
	v_ashrrev_i32_e32 v3, 31, v2
	v_lshl_add_u64 v[14:15], v[2:3], 2, s[80:81]
	v_ashrrev_i32_e32 v13, 31, v12
	v_mul_f32_e32 v2, 0x3c800000, v1
	v_pk_mul_f32 v[4:5], v[140:141], v[2:3] op_sel_hi:[1,0]
	v_pk_mul_f32 v[6:7], v[142:143], v[2:3] op_sel_hi:[1,0]
	v_pk_mul_f32 v[8:9], v[136:137], v[2:3] op_sel_hi:[1,0]
	v_pk_mul_f32 v[16:17], v[138:139], v[2:3] op_sel_hi:[1,0]
	v_pk_mul_f32 v[18:19], v[132:133], v[2:3] op_sel_hi:[1,0]
	v_pk_mul_f32 v[20:21], v[134:135], v[2:3] op_sel_hi:[1,0]
	v_pk_mul_f32 v[22:23], v[128:129], v[2:3] op_sel_hi:[1,0]
	v_pk_mul_f32 v[24:25], v[130:131], v[2:3] op_sel_hi:[1,0]
	v_cvt_pk_bf16_f32 v2, v4, v5
	v_cvt_pk_bf16_f32 v3, v6, v7
	v_cvt_pk_bf16_f32 v4, v8, v9
	v_cvt_pk_bf16_f32 v5, v16, v17
	v_cvt_pk_bf16_f32 v6, v18, v19
	v_cvt_pk_bf16_f32 v7, v20, v21
	v_cvt_pk_bf16_f32 v8, v22, v23
	v_cvt_pk_bf16_f32 v9, v24, v25
	v_permlane16_swap_b32_e32 v2, v4
	v_permlane16_swap_b32_e32 v3, v5
	v_permlane16_swap_b32_e32 v6, v8
	v_permlane16_swap_b32_e32 v7, v9
	global_store_dwordx4 v[10:11], v[2:5], off
	global_store_dwordx4 v[10:11], v[6:9], off offset:256
	v_mov_b32_e32 v1, v248
	v_add_u32_e32 v10, 0x90, v0
	v_lshrrev_b32_e32 v5, 5, v10
	v_lshlrev_b64 v[2:3], 11, v[12:13]
	v_and_b32_e32 v5, 0x7ffff0, v5
	v_and_b32_e32 v4, 0x1df, v10
	v_lshl_add_u64 v[2:3], s[56:57], 0, v[2:3]
	v_add_u32_e32 v5, s54, v5
	v_lshl_add_u64 v[12:13], v[2:3], 0, v[192:193]
	v_lshl_or_b32 v2, v5, 9, v4
	v_ashrrev_i32_e32 v3, 31, v2
	v_lshl_add_u64 v[14:15], v[2:3], 2, s[80:81]
	v_ashrrev_i32_e32 v11, 31, v10
	v_mul_f32_e32 v2, 0x3c800000, v1
	v_pk_mul_f32 v[4:5], v[124:125], v[2:3] op_sel_hi:[1,0]
	v_pk_mul_f32 v[6:7], v[126:127], v[2:3] op_sel_hi:[1,0]
	v_pk_mul_f32 v[8:9], v[120:121], v[2:3] op_sel_hi:[1,0]
	v_pk_mul_f32 v[16:17], v[122:123], v[2:3] op_sel_hi:[1,0]
	v_pk_mul_f32 v[18:19], v[116:117], v[2:3] op_sel_hi:[1,0]
	v_pk_mul_f32 v[20:21], v[118:119], v[2:3] op_sel_hi:[1,0]
	v_pk_mul_f32 v[22:23], v[112:113], v[2:3] op_sel_hi:[1,0]
	v_pk_mul_f32 v[24:25], v[114:115], v[2:3] op_sel_hi:[1,0]
	v_cvt_pk_bf16_f32 v2, v4, v5
	v_cvt_pk_bf16_f32 v3, v6, v7
; DEVI void ph_down(const Params& p, char* shm) {
;     ...
;         for (int m = 0; m < 4; ++m) {
;           int row = brow + ai * 128 + wr * 64 + m * 16 + fr;
;           int b = row >> 9, c = row & 511;
;           float gsc = selg[(b * 16 + e) * 512 + c] * (1.0f / W_DN_SCALE);
; #pragma unroll
;           for (int bj = 0; bj < 2; ++bj)
;             {
;               int col = bcol + bj * 128 + wc * 32 + (fq & 1) * 16 + (fq >> 1) * 8;
;               uint2 oa, ob;
;               oa.x = pack2(acc[ai][bj][m][0][0] * gsc, acc[ai][bj][m][0][1] * gsc);
;               oa.y = pack2(acc[ai][bj][m][0][2] * gsc, acc[ai][bj][m][0][3] * gsc);
;               ob.x = pack2(acc[ai][bj][m][1][0] * gsc, acc[ai][bj][m][1][1] * gsc);
;               ob.y = pack2(acc[ai][bj][m][1][2] * gsc, acc[ai][bj][m][1][3] * gsc);
;               *reinterpret_cast<uint4*>(Y + ((size_t)e * 4096 + row) * 1024 + col) = widen_pair(oa, ob);
;             }
	v_cvt_pk_bf16_f32 v4, v8, v9
	v_cvt_pk_bf16_f32 v5, v16, v17
	v_cvt_pk_bf16_f32 v6, v18, v19
	v_cvt_pk_bf16_f32 v7, v20, v21
	v_cvt_pk_bf16_f32 v8, v22, v23
	v_cvt_pk_bf16_f32 v9, v24, v25
	v_permlane16_swap_b32_e32 v2, v4
	v_permlane16_swap_b32_e32 v3, v5
	v_permlane16_swap_b32_e32 v6, v8
	v_permlane16_swap_b32_e32 v7, v9
	global_store_dwordx4 v[12:13], v[2:5], off
	global_store_dwordx4 v[12:13], v[6:9], off offset:256
	v_mov_b32_e32 v1, v249
	v_add_u32_e32 v12, 0xa0, v0
	v_lshrrev_b32_e32 v5, 5, v12
	v_lshlrev_b64 v[2:3], 11, v[10:11]
	v_and_b32_e32 v5, 0x7ffff0, v5
	v_and_b32_e32 v4, 0x1ef, v12
	v_lshl_add_u64 v[2:3], s[56:57], 0, v[2:3]
	v_add_u32_e32 v5, s54, v5
	v_lshl_add_u64 v[10:11], v[2:3], 0, v[192:193]
	v_lshl_or_b32 v2, v5, 9, v4
	v_ashrrev_i32_e32 v3, 31, v2
	v_lshl_add_u64 v[14:15], v[2:3], 2, s[80:81]
	v_ashrrev_i32_e32 v13, 31, v12
	v_mul_f32_e32 v2, 0x3c800000, v1
	v_pk_mul_f32 v[4:5], v[108:109], v[2:3] op_sel_hi:[1,0]
	v_pk_mul_f32 v[6:7], v[110:111], v[2:3] op_sel_hi:[1,0]
	v_pk_mul_f32 v[8:9], v[104:105], v[2:3] op_sel_hi:[1,0]
	v_pk_mul_f32 v[16:17], v[106:107], v[2:3] op_sel_hi:[1,0]
	v_pk_mul_f32 v[18:19], v[100:101], v[2:3] op_sel_hi:[1,0]
	v_pk_mul_f32 v[20:21], v[102:103], v[2:3] op_sel_hi:[1,0]
	v_pk_mul_f32 v[22:23], v[96:97], v[2:3] op_sel_hi:[1,0]
	v_pk_mul_f32 v[24:25], v[98:99], v[2:3] op_sel_hi:[1,0]
	v_cvt_pk_bf16_f32 v2, v4, v5
	v_cvt_pk_bf16_f32 v3, v6, v7
	v_cvt_pk_bf16_f32 v4, v8, v9
	v_cvt_pk_bf16_f32 v5, v16, v17
	v_cvt_pk_bf16_f32 v6, v18, v19
	v_cvt_pk_bf16_f32 v7, v20, v21
	v_cvt_pk_bf16_f32 v8, v22, v23
	v_cvt_pk_bf16_f32 v9, v24, v25
	v_permlane16_swap_b32_e32 v2, v4
	v_permlane16_swap_b32_e32 v3, v5
	v_permlane16_swap_b32_e32 v6, v8
	v_permlane16_swap_b32_e32 v7, v9
	global_store_dwordx4 v[10:11], v[2:5], off
	global_store_dwordx4 v[10:11], v[6:9], off offset:256
	v_mov_b32_e32 v2, v250
	s_nop 0
	v_add_u32_e32 v8, 0xb0, v0
	v_lshrrev_b32_e32 v4, 5, v8
	v_lshlrev_b64 v[0:1], 11, v[12:13]
	v_and_b32_e32 v4, 0x7ffff0, v4
	v_and_b32_e32 v3, 0x1ff, v8
	v_lshl_add_u64 v[0:1], s[56:57], 0, v[0:1]
	v_add_u32_e32 v4, s54, v4
	v_lshl_add_u64 v[10:11], v[0:1], 0, v[192:193]
	v_lshl_or_b32 v0, v4, 9, v3
	v_ashrrev_i32_e32 v1, 31, v0
	v_lshl_add_u64 v[12:13], v[0:1], 2, s[80:81]
	v_ashrrev_i32_e32 v9, 31, v8
	v_mul_f32_e32 v0, 0x3c800000, v2
	v_pk_mul_f32 v[2:3], v[92:93], v[0:1] op_sel_hi:[1,0]
	v_pk_mul_f32 v[4:5], v[94:95], v[0:1] op_sel_hi:[1,0]
	v_pk_mul_f32 v[6:7], v[88:89], v[0:1] op_sel_hi:[1,0]
	v_pk_mul_f32 v[14:15], v[90:91], v[0:1] op_sel_hi:[1,0]
	v_pk_mul_f32 v[16:17], v[84:85], v[0:1] op_sel_hi:[1,0]
	v_pk_mul_f32 v[18:19], v[86:87], v[0:1] op_sel_hi:[1,0]
	v_pk_mul_f32 v[20:21], v[80:81], v[0:1] op_sel_hi:[1,0]
	v_pk_mul_f32 v[22:23], v[82:83], v[0:1] op_sel_hi:[1,0]
	v_cvt_pk_bf16_f32 v0, v2, v3
	v_cvt_pk_bf16_f32 v1, v4, v5
	v_cvt_pk_bf16_f32 v2, v6, v7
	v_cvt_pk_bf16_f32 v3, v14, v15
	v_cvt_pk_bf16_f32 v4, v16, v17
	v_cvt_pk_bf16_f32 v5, v18, v19
	v_cvt_pk_bf16_f32 v6, v20, v21
	v_cvt_pk_bf16_f32 v7, v22, v23
	v_permlane16_swap_b32_e32 v0, v2
	v_permlane16_swap_b32_e32 v1, v3
	v_permlane16_swap_b32_e32 v4, v6
	v_permlane16_swap_b32_e32 v5, v7
	global_store_dwordx4 v[10:11], v[0:3], off
	global_store_dwordx4 v[10:11], v[4:7], off offset:256
	v_mov_b32_e32 v2, v251
	v_lshlrev_b64 v[0:1], 11, v[8:9]
	v_lshl_add_u64 v[0:1], s[56:57], 0, v[0:1]
	v_lshl_add_u64 v[8:9], v[0:1], 0, v[192:193]
	v_mul_f32_e32 v0, 0x3c800000, v2
	v_pk_mul_f32 v[2:3], v[76:77], v[0:1] op_sel_hi:[1,0]
	v_pk_mul_f32 v[4:5], v[78:79], v[0:1] op_sel_hi:[1,0]
	v_pk_mul_f32 v[6:7], v[72:73], v[0:1] op_sel_hi:[1,0]
	v_pk_mul_f32 v[10:11], v[74:75], v[0:1] op_sel_hi:[1,0]
	v_pk_mul_f32 v[12:13], v[68:69], v[0:1] op_sel_hi:[1,0]
	v_pk_mul_f32 v[14:15], v[70:71], v[0:1] op_sel_hi:[1,0]
	v_pk_mul_f32 v[16:17], v[64:65], v[0:1] op_sel_hi:[1,0]
	v_pk_mul_f32 v[18:19], v[66:67], v[0:1] op_sel_hi:[1,0]
	v_cvt_pk_bf16_f32 v0, v2, v3
	v_cvt_pk_bf16_f32 v1, v4, v5
	v_cvt_pk_bf16_f32 v2, v6, v7
	v_cvt_pk_bf16_f32 v3, v10, v11
	v_cvt_pk_bf16_f32 v4, v12, v13
	v_cvt_pk_bf16_f32 v5, v14, v15
	v_cvt_pk_bf16_f32 v6, v16, v17
	v_cvt_pk_bf16_f32 v7, v18, v19
	v_permlane16_swap_b32_e32 v0, v2
	v_permlane16_swap_b32_e32 v1, v3
	v_permlane16_swap_b32_e32 v4, v6
	v_permlane16_swap_b32_e32 v5, v7
	global_store_dwordx4 v[8:9], v[0:3], off
	global_store_dwordx4 v[8:9], v[4:7], off offset:256
	s_cbranch_vccz .LBB0_2122
